# G1 rotary epilogue: cos/sin of the next row group prefetched one row group ahead into spare registers (no store-drain wait before each rotation)
# baseline (speedup 1.0000x reference)
.LBB0_364:
	v_pk_mul_f32 v[166:167], v[160:161], v[124:125] op_sel_hi:[0,1]
	v_cndmask_b32_e64 v124, 0, 1, s[40:41]
	v_pk_mul_f32 v[168:169], v[160:161], v[128:129] op_sel_hi:[0,1]
	v_pk_mul_f32 v[126:127], v[160:161], v[126:127] op_sel_hi:[0,1]
	v_cmp_ne_u32_e64 s[36:37], 1, v124
	s_andn2_b64 vcc, exec, s[40:41]
	v_pk_mul_f32 v[128:129], v[160:161], v[122:123] op_sel_hi:[0,1]
	s_mov_b32 s26, 0x2aaaaaab
	s_cbranch_vccnz .LBB0_366
	s_waitcnt vmcnt(0)
	v_or_b32_e32 v240, 16, v164
	v_ashrrev_i32_e32 v241, 31, v240
	v_lshlrev_b64 v[240:241], 8, v[240:241]
	v_lshl_add_u64 v[240:241], v[146:147], 0, v[240:241]
	global_load_dwordx4 v[248:251], v[240:241], off
	global_load_dwordx4 v[252:255], v[240:241], off offset:16
	v_pk_mul_f32 v[124:125], v[126:127], v[134:135] op_sel:[1,1] op_sel_hi:[0,1]
	v_pk_mul_f32 v[122:123], v[126:127], v[134:135]
	v_pk_fma_f32 v[126:127], v[126:127], v[134:135], v[124:125] op_sel_hi:[1,0,1]
	v_pk_mul_f32 v[186:187], v[128:129], v[130:131] op_sel:[1,1] op_sel_hi:[0,1]
	v_mul_f32_e32 v126, v169, v137
	v_pk_fma_f32 v[182:183], v[168:169], v[136:137], v[126:127] op_sel_hi:[1,1,0] neg_lo:[0,0,1] neg_hi:[0,0,1]
	v_mul_f32_e32 v126, v168, v137
	v_pk_fma_f32 v[184:185], v[168:169], v[136:137], v[126:127] op_sel:[1,0,0] op_sel_hi:[0,1,0]
	v_mul_f32_e32 v126, v167, v133
	v_pk_fma_f32 v[188:189], v[166:167], v[132:133], v[126:127] op_sel_hi:[1,1,0] neg_lo:[0,0,1] neg_hi:[0,0,1]
	v_mul_f32_e32 v126, v166, v133
	v_pk_mul_f32 v[168:169], v[128:129], v[130:131]
	v_pk_fma_f32 v[128:129], v[128:129], v[130:131], v[186:187] op_sel_hi:[1,0,1]
	v_pk_fma_f32 v[190:191], v[166:167], v[132:133], v[126:127] op_sel:[1,0,0] op_sel_hi:[0,1,0]
	v_sub_f32_e32 v126, v122, v124
	v_sub_f32_e32 v128, v168, v186
	v_mov_b32_e32 v168, v182
	v_mov_b32_e32 v169, v184
	v_mov_b32_e32 v166, v188
	v_mov_b32_e32 v167, v190
.LBB0_366:
	v_readlane_b32 s8, v245, 21
	v_readlane_b32 s9, v245, 22
	v_lshl_or_b32 v122, s22, 8, v180
	v_ashrrev_i32_e32 v123, 31, v122
	v_mov_b64_e32 v[124:125], s[8:9]
	v_mad_i64_i32 v[124:125], s[8:9], v164, s33, v[124:125]
	v_lshl_add_u64 v[124:125], v[122:123], 1, v[124:125]
	v_cvt_pk_bf16_f32 v126, v126, v127
	v_cvt_pk_bf16_f32 v127, v168, v169
	v_mov_b32_e32 v182, v160
	v_mov_b32_e32 v183, v160
	v_cvt_pk_bf16_f32 v128, v128, v129
	v_cvt_pk_bf16_f32 v129, v166, v167
	global_store_dwordx4 v[124:125], v[126:129], off
	v_pk_mul_f32 v[118:119], v[182:183], v[118:119]
	s_and_b64 vcc, exec, s[36:37]
	v_mov_b32_e32 v126, v160
	v_mov_b32_e32 v127, v160
	v_pk_mul_f32 v[120:121], v[126:127], v[120:121]
	v_pk_mul_f32 v[116:117], v[126:127], v[116:117]
	v_pk_mul_f32 v[114:115], v[182:183], v[114:115]
	s_cbranch_vccnz .LBB0_368
	s_nop 0
	v_pk_mul_f32 v[128:129], v[118:119], v[134:135] op_sel:[1,1] op_sel_hi:[0,1]
	v_pk_mul_f32 v[126:127], v[118:119], v[134:135]
	v_pk_fma_f32 v[118:119], v[118:119], v[134:135], v[128:129] op_sel_hi:[1,0,1]
	v_pk_mul_f32 v[166:167], v[114:115], v[130:131] op_sel:[1,1] op_sel_hi:[0,1]
	v_mul_f32_e32 v118, v121, v137
	v_pk_fma_f32 v[134:135], v[120:121], v[136:137], v[118:119] op_sel_hi:[1,1,0] neg_lo:[0,0,1] neg_hi:[0,0,1]
	v_mul_f32_e32 v118, v120, v137
	v_pk_fma_f32 v[136:137], v[120:121], v[136:137], v[118:119] op_sel:[1,0,0] op_sel_hi:[0,1,0]
	v_pk_mul_f32 v[120:121], v[114:115], v[130:131]
	v_pk_fma_f32 v[114:115], v[114:115], v[130:131], v[166:167] op_sel_hi:[1,0,1]
	v_sub_f32_e32 v118, v126, v128
	v_mul_f32_e32 v114, v117, v133
	v_pk_fma_f32 v[130:131], v[116:117], v[132:133], v[114:115] op_sel_hi:[1,1,0] neg_lo:[0,0,1] neg_hi:[0,0,1]
	v_mul_f32_e32 v114, v116, v133
	v_pk_fma_f32 v[132:133], v[116:117], v[132:133], v[114:115] op_sel:[1,0,0] op_sel_hi:[0,1,0]
	v_sub_f32_e32 v114, v120, v166
	v_mov_b32_e32 v120, v134
	v_mov_b32_e32 v121, v136
	v_mov_b32_e32 v116, v130
	v_mov_b32_e32 v117, v132
.LBB0_368:
	v_cvt_pk_bf16_f32 v118, v118, v119
	v_cvt_pk_bf16_f32 v119, v120, v121
	v_cvt_pk_bf16_f32 v120, v114, v115
	v_cvt_pk_bf16_f32 v121, v116, v117
	global_store_dwordx4 v[124:125], v[118:121], off offset:256
	v_or_b32_e32 v124, 16, v164
	s_and_b64 vcc, exec, s[36:37]
	v_ashrrev_i32_e32 v125, 31, v124
	s_cbranch_vccnz .LBB0_370
	s_waitcnt vmcnt(2)
	v_mov_b32_e32 v118, v248
	v_mov_b32_e32 v119, v249
	v_mov_b32_e32 v120, v250
	v_mov_b32_e32 v121, v251
	v_mov_b32_e32 v114, v252
	v_mov_b32_e32 v115, v253
	v_mov_b32_e32 v116, v254
	v_mov_b32_e32 v117, v255
	s_branch .LBB0_371

.LBB0_371:
	v_pk_mul_f32 v[126:127], v[160:161], v[112:113] op_sel:[1,0]
	v_pk_mul_f32 v[110:111], v[160:161], v[110:111] op_sel:[1,0]
	v_pk_mul_f32 v[112:113], v[160:161], v[108:109] op_sel:[1,0]
	s_and_b64 vcc, exec, s[36:37]
	v_pk_mul_f32 v[108:109], v[160:161], v[106:107] op_sel:[1,0]
	s_cbranch_vccnz .LBB0_373
	v_or_b32_e32 v240, 32, v164
	v_ashrrev_i32_e32 v241, 31, v240
	v_lshlrev_b64 v[240:241], 8, v[240:241]
	v_lshl_add_u64 v[240:241], v[146:147], 0, v[240:241]
	global_load_dwordx4 v[248:251], v[240:241], off
	global_load_dwordx4 v[252:255], v[240:241], off offset:16
	v_pk_mul_f32 v[128:129], v[110:111], v[118:119] op_sel:[1,1] op_sel_hi:[0,1]
	v_pk_mul_f32 v[106:107], v[110:111], v[118:119]
	v_pk_fma_f32 v[110:111], v[110:111], v[118:119], v[128:129] op_sel_hi:[1,0,1]
	v_pk_mul_f32 v[134:135], v[108:109], v[114:115] op_sel:[1,1] op_sel_hi:[0,1]
	v_mul_f32_e32 v110, v127, v121
	v_pk_fma_f32 v[130:131], v[126:127], v[120:121], v[110:111] op_sel_hi:[1,1,0] neg_lo:[0,0,1] neg_hi:[0,0,1]
	v_mul_f32_e32 v110, v126, v121
	v_pk_fma_f32 v[132:133], v[126:127], v[120:121], v[110:111] op_sel:[1,0,0] op_sel_hi:[0,1,0]
	v_pk_mul_f32 v[126:127], v[108:109], v[114:115]
	v_pk_fma_f32 v[108:109], v[108:109], v[114:115], v[134:135] op_sel_hi:[1,0,1]
	v_sub_f32_e32 v110, v106, v128
	v_mul_f32_e32 v108, v113, v117
	v_pk_fma_f32 v[136:137], v[112:113], v[116:117], v[108:109] op_sel_hi:[1,1,0] neg_lo:[0,0,1] neg_hi:[0,0,1]
	v_mul_f32_e32 v108, v112, v117
	v_pk_fma_f32 v[166:167], v[112:113], v[116:117], v[108:109] op_sel:[1,0,0] op_sel_hi:[0,1,0]
	v_sub_f32_e32 v108, v126, v134
	v_mov_b32_e32 v126, v130
	v_mov_b32_e32 v127, v132
	v_mov_b32_e32 v112, v136
	v_mov_b32_e32 v113, v166
.LBB0_373:
	v_readlane_b32 s8, v245, 21
	v_readlane_b32 s9, v245, 22
	v_mov_b32_e32 v160, v161
	v_pk_mul_f32 v[102:103], v[160:161], v[102:103]
	v_mov_b64_e32 v[106:107], s[8:9]
	v_mad_i64_i32 v[106:107], s[8:9], v124, s33, v[106:107]
	v_cvt_pk_bf16_f32 v124, v110, v111
	v_cvt_pk_bf16_f32 v125, v126, v127
	v_cvt_pk_bf16_f32 v126, v108, v109
	v_mov_b32_e32 v108, v161
	v_mov_b32_e32 v109, v161
	v_lshl_add_u64 v[106:107], v[122:123], 1, v[106:107]
	v_pk_mul_f32 v[104:105], v[108:109], v[104:105]
	v_pk_mul_f32 v[100:101], v[108:109], v[100:101]
	s_and_b64 vcc, exec, s[36:37]
	v_pk_mul_f32 v[98:99], v[160:161], v[98:99]
	v_cvt_pk_bf16_f32 v127, v112, v113
	global_store_dwordx4 v[106:107], v[124:127], off
	s_cbranch_vccnz .LBB0_375
	s_nop 0
	v_pk_mul_f32 v[110:111], v[102:103], v[118:119] op_sel:[1,1] op_sel_hi:[0,1]
	v_pk_mul_f32 v[108:109], v[102:103], v[118:119]
	v_pk_fma_f32 v[102:103], v[102:103], v[118:119], v[110:111] op_sel_hi:[1,0,1]
	s_nop 0
	v_mul_f32_e32 v102, v105, v121
	v_pk_fma_f32 v[112:113], v[104:105], v[120:121], v[102:103] op_sel_hi:[1,1,0] neg_lo:[0,0,1] neg_hi:[0,0,1]
	v_mul_f32_e32 v102, v104, v121
	v_pk_fma_f32 v[118:119], v[104:105], v[120:121], v[102:103] op_sel:[1,0,0] op_sel_hi:[0,1,0]
	v_pk_mul_f32 v[120:121], v[98:99], v[114:115] op_sel:[1,1] op_sel_hi:[0,1]
	v_pk_mul_f32 v[104:105], v[98:99], v[114:115]
	v_pk_fma_f32 v[98:99], v[98:99], v[114:115], v[120:121] op_sel_hi:[1,0,1]
	v_sub_f32_e32 v102, v108, v110
	v_mul_f32_e32 v98, v101, v117
	v_pk_fma_f32 v[114:115], v[100:101], v[116:117], v[98:99] op_sel_hi:[1,1,0] neg_lo:[0,0,1] neg_hi:[0,0,1]
	v_mul_f32_e32 v98, v100, v117
	v_pk_fma_f32 v[116:117], v[100:101], v[116:117], v[98:99] op_sel:[1,0,0] op_sel_hi:[0,1,0]
	v_sub_f32_e32 v98, v104, v120
	v_mov_b32_e32 v104, v112
	v_mov_b32_e32 v105, v118
	v_mov_b32_e32 v100, v114
	v_mov_b32_e32 v101, v116
.LBB0_375:
	v_cvt_pk_bf16_f32 v102, v102, v103
	v_cvt_pk_bf16_f32 v103, v104, v105
	v_cvt_pk_bf16_f32 v104, v98, v99
	v_cvt_pk_bf16_f32 v105, v100, v101
	global_store_dwordx4 v[106:107], v[102:105], off offset:256
	v_or_b32_e32 v106, 32, v164
	s_and_b64 vcc, exec, s[36:37]
	v_ashrrev_i32_e32 v107, 31, v106
	s_cbranch_vccnz .LBB0_377
	s_waitcnt vmcnt(2)
	v_mov_b32_e32 v102, v248
	v_mov_b32_e32 v103, v249
	v_mov_b32_e32 v104, v250
	v_mov_b32_e32 v105, v251
	v_mov_b32_e32 v98, v252
	v_mov_b32_e32 v99, v253
	v_mov_b32_e32 v100, v254
	v_mov_b32_e32 v101, v255
	s_branch .LBB0_378

.LBB0_378:
	v_pk_mul_f32 v[108:109], v[158:159], v[96:97] op_sel_hi:[0,1]
	v_pk_mul_f32 v[94:95], v[158:159], v[94:95] op_sel_hi:[0,1]
	v_pk_mul_f32 v[96:97], v[158:159], v[92:93] op_sel_hi:[0,1]
	s_and_b64 vcc, exec, s[36:37]
	v_pk_mul_f32 v[92:93], v[158:159], v[90:91] op_sel_hi:[0,1]
	s_cbranch_vccnz .LBB0_380
	v_or_b32_e32 v240, 48, v164
	v_ashrrev_i32_e32 v241, 31, v240
	v_lshlrev_b64 v[240:241], 8, v[240:241]
	v_lshl_add_u64 v[240:241], v[146:147], 0, v[240:241]
	global_load_dwordx4 v[248:251], v[240:241], off
	global_load_dwordx4 v[252:255], v[240:241], off offset:16
	v_pk_mul_f32 v[110:111], v[94:95], v[102:103] op_sel:[1,1] op_sel_hi:[0,1]
	v_pk_mul_f32 v[90:91], v[94:95], v[102:103]
	v_pk_fma_f32 v[94:95], v[94:95], v[102:103], v[110:111] op_sel_hi:[1,0,1]
	v_pk_mul_f32 v[116:117], v[92:93], v[98:99] op_sel:[1,1] op_sel_hi:[0,1]
	v_mul_f32_e32 v94, v109, v105
	v_pk_fma_f32 v[112:113], v[108:109], v[104:105], v[94:95] op_sel_hi:[1,1,0] neg_lo:[0,0,1] neg_hi:[0,0,1]
	v_mul_f32_e32 v94, v108, v105
	v_pk_fma_f32 v[114:115], v[108:109], v[104:105], v[94:95] op_sel:[1,0,0] op_sel_hi:[0,1,0]
	v_pk_mul_f32 v[108:109], v[92:93], v[98:99]
	v_pk_fma_f32 v[92:93], v[92:93], v[98:99], v[116:117] op_sel_hi:[1,0,1]
	v_sub_f32_e32 v94, v90, v110
	v_mul_f32_e32 v92, v97, v101
	v_pk_fma_f32 v[118:119], v[96:97], v[100:101], v[92:93] op_sel_hi:[1,1,0] neg_lo:[0,0,1] neg_hi:[0,0,1]
	v_mul_f32_e32 v92, v96, v101
	v_pk_fma_f32 v[120:121], v[96:97], v[100:101], v[92:93] op_sel:[1,0,0] op_sel_hi:[0,1,0]
	v_sub_f32_e32 v92, v108, v116
	v_mov_b32_e32 v108, v112
	v_mov_b32_e32 v109, v114
	v_mov_b32_e32 v96, v118
	v_mov_b32_e32 v97, v120
.LBB0_380:
	v_readlane_b32 s8, v245, 21
	v_readlane_b32 s9, v245, 22
	v_mov_b32_e32 v159, v158
	v_pk_mul_f32 v[86:87], v[158:159], v[86:87]
	v_mov_b64_e32 v[90:91], s[8:9]
	v_mad_i64_i32 v[90:91], s[8:9], v106, s33, v[90:91]
	v_cvt_pk_bf16_f32 v106, v94, v95
	v_cvt_pk_bf16_f32 v107, v108, v109
	v_cvt_pk_bf16_f32 v108, v92, v93
	v_mov_b32_e32 v92, v158
	v_mov_b32_e32 v93, v158
	v_lshl_add_u64 v[90:91], v[122:123], 1, v[90:91]
	v_pk_mul_f32 v[88:89], v[92:93], v[88:89]
	v_pk_mul_f32 v[84:85], v[92:93], v[84:85]
	s_and_b64 vcc, exec, s[36:37]
	v_pk_mul_f32 v[82:83], v[158:159], v[82:83]
	v_cvt_pk_bf16_f32 v109, v96, v97
	global_store_dwordx4 v[90:91], v[106:109], off
	s_cbranch_vccnz .LBB0_382
	s_nop 0
	v_pk_mul_f32 v[94:95], v[86:87], v[102:103] op_sel:[1,1] op_sel_hi:[0,1]
	v_pk_mul_f32 v[92:93], v[86:87], v[102:103]
	v_pk_fma_f32 v[86:87], v[86:87], v[102:103], v[94:95] op_sel_hi:[1,0,1]
	s_nop 0
	v_mul_f32_e32 v86, v89, v105
	v_pk_fma_f32 v[96:97], v[88:89], v[104:105], v[86:87] op_sel_hi:[1,1,0] neg_lo:[0,0,1] neg_hi:[0,0,1]
	v_mul_f32_e32 v86, v88, v105
	v_pk_fma_f32 v[102:103], v[88:89], v[104:105], v[86:87] op_sel:[1,0,0] op_sel_hi:[0,1,0]
	v_pk_mul_f32 v[104:105], v[82:83], v[98:99] op_sel:[1,1] op_sel_hi:[0,1]
	v_pk_mul_f32 v[88:89], v[82:83], v[98:99]
	v_pk_fma_f32 v[82:83], v[82:83], v[98:99], v[104:105] op_sel_hi:[1,0,1]
	v_sub_f32_e32 v86, v92, v94
	v_mul_f32_e32 v82, v85, v101
	v_pk_fma_f32 v[98:99], v[84:85], v[100:101], v[82:83] op_sel_hi:[1,1,0] neg_lo:[0,0,1] neg_hi:[0,0,1]
	v_mul_f32_e32 v82, v84, v101
	v_pk_fma_f32 v[100:101], v[84:85], v[100:101], v[82:83] op_sel:[1,0,0] op_sel_hi:[0,1,0]
	v_sub_f32_e32 v82, v88, v104
	v_mov_b32_e32 v88, v96
	v_mov_b32_e32 v89, v102
	v_mov_b32_e32 v84, v98
	v_mov_b32_e32 v85, v100
.LBB0_382:
	v_cvt_pk_bf16_f32 v86, v86, v87
	v_cvt_pk_bf16_f32 v87, v88, v89
	v_cvt_pk_bf16_f32 v88, v82, v83
	v_cvt_pk_bf16_f32 v89, v84, v85
	global_store_dwordx4 v[90:91], v[86:89], off offset:256
	v_or_b32_e32 v90, 48, v164
	s_and_b64 vcc, exec, s[36:37]
	v_ashrrev_i32_e32 v91, 31, v90
	s_cbranch_vccnz .LBB0_384
	s_waitcnt vmcnt(2)
	v_mov_b32_e32 v86, v248
	v_mov_b32_e32 v87, v249
	v_mov_b32_e32 v88, v250
	v_mov_b32_e32 v89, v251
	v_mov_b32_e32 v82, v252
	v_mov_b32_e32 v83, v253
	v_mov_b32_e32 v84, v254
	v_mov_b32_e32 v85, v255
	s_branch .LBB0_385

.LBB0_385:
	v_pk_mul_f32 v[92:93], v[156:157], v[80:81] op_sel_hi:[0,1]
	v_pk_mul_f32 v[78:79], v[156:157], v[78:79] op_sel_hi:[0,1]
	v_pk_mul_f32 v[80:81], v[156:157], v[76:77] op_sel_hi:[0,1]
	s_and_b64 vcc, exec, s[36:37]
	v_pk_mul_f32 v[76:77], v[156:157], v[74:75] op_sel_hi:[0,1]
	s_cbranch_vccnz .LBB0_387
	v_add_u32_e32 v240, 0x80, v164
	v_ashrrev_i32_e32 v241, 31, v240
	v_lshlrev_b64 v[240:241], 8, v[240:241]
	v_lshl_add_u64 v[240:241], v[146:147], 0, v[240:241]
	global_load_dwordx4 v[248:251], v[240:241], off
	global_load_dwordx4 v[252:255], v[240:241], off offset:16
	v_pk_mul_f32 v[94:95], v[78:79], v[86:87] op_sel:[1,1] op_sel_hi:[0,1]
	v_pk_mul_f32 v[74:75], v[78:79], v[86:87]
	v_pk_fma_f32 v[78:79], v[78:79], v[86:87], v[94:95] op_sel_hi:[1,0,1]
	v_pk_mul_f32 v[100:101], v[76:77], v[82:83] op_sel:[1,1] op_sel_hi:[0,1]
	v_mul_f32_e32 v78, v93, v89
	v_pk_fma_f32 v[96:97], v[92:93], v[88:89], v[78:79] op_sel_hi:[1,1,0] neg_lo:[0,0,1] neg_hi:[0,0,1]
	v_mul_f32_e32 v78, v92, v89
	v_pk_fma_f32 v[98:99], v[92:93], v[88:89], v[78:79] op_sel:[1,0,0] op_sel_hi:[0,1,0]
	v_pk_mul_f32 v[92:93], v[76:77], v[82:83]
	v_pk_fma_f32 v[76:77], v[76:77], v[82:83], v[100:101] op_sel_hi:[1,0,1]
	v_sub_f32_e32 v78, v74, v94
	v_mul_f32_e32 v76, v81, v85
	v_pk_fma_f32 v[102:103], v[80:81], v[84:85], v[76:77] op_sel_hi:[1,1,0] neg_lo:[0,0,1] neg_hi:[0,0,1]
	v_mul_f32_e32 v76, v80, v85
	v_pk_fma_f32 v[104:105], v[80:81], v[84:85], v[76:77] op_sel:[1,0,0] op_sel_hi:[0,1,0]
	v_sub_f32_e32 v76, v92, v100
	v_mov_b32_e32 v92, v96
	v_mov_b32_e32 v93, v98
	v_mov_b32_e32 v80, v102
	v_mov_b32_e32 v81, v104
.LBB0_387:
	v_readlane_b32 s8, v245, 21
	v_readlane_b32 s9, v245, 22
	v_mov_b32_e32 v157, v156
	v_pk_mul_f32 v[70:71], v[156:157], v[70:71]
	v_mov_b64_e32 v[74:75], s[8:9]
	v_mad_i64_i32 v[74:75], s[8:9], v90, s33, v[74:75]
	v_cvt_pk_bf16_f32 v90, v78, v79
	v_cvt_pk_bf16_f32 v91, v92, v93
	v_cvt_pk_bf16_f32 v92, v76, v77
	v_mov_b32_e32 v76, v156
	v_mov_b32_e32 v77, v156
	v_lshl_add_u64 v[74:75], v[122:123], 1, v[74:75]
	v_pk_mul_f32 v[72:73], v[76:77], v[72:73]
	v_pk_mul_f32 v[68:69], v[76:77], v[68:69]
	s_and_b64 vcc, exec, s[36:37]
	v_pk_mul_f32 v[66:67], v[156:157], v[66:67]
	v_cvt_pk_bf16_f32 v93, v80, v81
	global_store_dwordx4 v[74:75], v[90:93], off
	s_cbranch_vccnz .LBB0_389
	s_nop 0
	v_pk_mul_f32 v[78:79], v[70:71], v[86:87] op_sel:[1,1] op_sel_hi:[0,1]
	v_pk_mul_f32 v[76:77], v[70:71], v[86:87]
	v_pk_fma_f32 v[70:71], v[70:71], v[86:87], v[78:79] op_sel_hi:[1,0,1]
	s_nop 0
	v_mul_f32_e32 v70, v73, v89
	v_pk_fma_f32 v[80:81], v[72:73], v[88:89], v[70:71] op_sel_hi:[1,1,0] neg_lo:[0,0,1] neg_hi:[0,0,1]
	v_mul_f32_e32 v70, v72, v89
	v_pk_fma_f32 v[86:87], v[72:73], v[88:89], v[70:71] op_sel:[1,0,0] op_sel_hi:[0,1,0]
	v_pk_mul_f32 v[88:89], v[66:67], v[82:83] op_sel:[1,1] op_sel_hi:[0,1]
	v_pk_mul_f32 v[72:73], v[66:67], v[82:83]
	v_pk_fma_f32 v[66:67], v[66:67], v[82:83], v[88:89] op_sel_hi:[1,0,1]
	v_sub_f32_e32 v70, v76, v78
	v_mul_f32_e32 v66, v69, v85
	v_pk_fma_f32 v[82:83], v[68:69], v[84:85], v[66:67] op_sel_hi:[1,1,0] neg_lo:[0,0,1] neg_hi:[0,0,1]
	v_mul_f32_e32 v66, v68, v85
	v_pk_fma_f32 v[84:85], v[68:69], v[84:85], v[66:67] op_sel:[1,0,0] op_sel_hi:[0,1,0]
	v_sub_f32_e32 v66, v72, v88
	v_mov_b32_e32 v72, v80
	v_mov_b32_e32 v73, v86
	v_mov_b32_e32 v68, v82
	v_mov_b32_e32 v69, v84
.LBB0_389:
	v_cvt_pk_bf16_f32 v70, v70, v71
	v_cvt_pk_bf16_f32 v71, v72, v73
	v_cvt_pk_bf16_f32 v72, v66, v67
	v_cvt_pk_bf16_f32 v73, v68, v69
	global_store_dwordx4 v[74:75], v[70:73], off offset:256
	v_add_u32_e32 v74, 0x80, v164
	s_and_b64 vcc, exec, s[36:37]
	v_ashrrev_i32_e32 v75, 31, v74
	s_cbranch_vccnz .LBB0_391
	s_waitcnt vmcnt(2)
	v_mov_b32_e32 v70, v248
	v_mov_b32_e32 v71, v249
	v_mov_b32_e32 v72, v250
	v_mov_b32_e32 v73, v251
	v_mov_b32_e32 v66, v252
	v_mov_b32_e32 v67, v253
	v_mov_b32_e32 v68, v254
	v_mov_b32_e32 v69, v255
	s_branch .LBB0_392

.LBB0_392:
	v_pk_mul_f32 v[76:77], v[154:155], v[64:65] op_sel_hi:[0,1]
	v_pk_mul_f32 v[62:63], v[154:155], v[62:63] op_sel_hi:[0,1]
	v_pk_mul_f32 v[64:65], v[154:155], v[60:61] op_sel_hi:[0,1]
	s_and_b64 vcc, exec, s[36:37]
	v_pk_mul_f32 v[60:61], v[154:155], v[58:59] op_sel_hi:[0,1]
	s_cbranch_vccnz .LBB0_394
	v_add_u32_e32 v240, 0x90, v164
	v_ashrrev_i32_e32 v241, 31, v240
	v_lshlrev_b64 v[240:241], 8, v[240:241]
	v_lshl_add_u64 v[240:241], v[146:147], 0, v[240:241]
	global_load_dwordx4 v[248:251], v[240:241], off
	global_load_dwordx4 v[252:255], v[240:241], off offset:16
	v_pk_mul_f32 v[78:79], v[62:63], v[70:71] op_sel:[1,1] op_sel_hi:[0,1]
	v_pk_mul_f32 v[58:59], v[62:63], v[70:71]
	v_pk_fma_f32 v[62:63], v[62:63], v[70:71], v[78:79] op_sel_hi:[1,0,1]
	v_pk_mul_f32 v[84:85], v[60:61], v[66:67] op_sel:[1,1] op_sel_hi:[0,1]
	v_mul_f32_e32 v62, v77, v73
	v_pk_fma_f32 v[80:81], v[76:77], v[72:73], v[62:63] op_sel_hi:[1,1,0] neg_lo:[0,0,1] neg_hi:[0,0,1]
	v_mul_f32_e32 v62, v76, v73
	v_pk_fma_f32 v[82:83], v[76:77], v[72:73], v[62:63] op_sel:[1,0,0] op_sel_hi:[0,1,0]
	v_pk_mul_f32 v[76:77], v[60:61], v[66:67]
	v_pk_fma_f32 v[60:61], v[60:61], v[66:67], v[84:85] op_sel_hi:[1,0,1]
	v_sub_f32_e32 v62, v58, v78
	v_mul_f32_e32 v60, v65, v69
	v_pk_fma_f32 v[86:87], v[64:65], v[68:69], v[60:61] op_sel_hi:[1,1,0] neg_lo:[0,0,1] neg_hi:[0,0,1]
	v_mul_f32_e32 v60, v64, v69
	v_pk_fma_f32 v[88:89], v[64:65], v[68:69], v[60:61] op_sel:[1,0,0] op_sel_hi:[0,1,0]
	v_sub_f32_e32 v60, v76, v84
	v_mov_b32_e32 v76, v80
	v_mov_b32_e32 v77, v82
	v_mov_b32_e32 v64, v86
	v_mov_b32_e32 v65, v88
.LBB0_394:
	v_readlane_b32 s8, v245, 21
	v_readlane_b32 s9, v245, 22
	v_mov_b32_e32 v155, v154
	v_pk_mul_f32 v[54:55], v[154:155], v[54:55]
	v_mov_b64_e32 v[58:59], s[8:9]
	v_mad_i64_i32 v[58:59], s[8:9], v74, s33, v[58:59]
	v_cvt_pk_bf16_f32 v74, v62, v63
	v_cvt_pk_bf16_f32 v75, v76, v77
	v_cvt_pk_bf16_f32 v76, v60, v61
	v_mov_b32_e32 v60, v154
	v_mov_b32_e32 v61, v154
	v_lshl_add_u64 v[58:59], v[122:123], 1, v[58:59]
	v_pk_mul_f32 v[56:57], v[60:61], v[56:57]
	v_pk_mul_f32 v[52:53], v[60:61], v[52:53]
	s_and_b64 vcc, exec, s[36:37]
	v_pk_mul_f32 v[50:51], v[154:155], v[50:51]
	v_cvt_pk_bf16_f32 v77, v64, v65
	global_store_dwordx4 v[58:59], v[74:77], off
	s_cbranch_vccnz .LBB0_396
	s_nop 0
	v_pk_mul_f32 v[62:63], v[54:55], v[70:71] op_sel:[1,1] op_sel_hi:[0,1]
	v_pk_mul_f32 v[60:61], v[54:55], v[70:71]
	v_pk_fma_f32 v[54:55], v[54:55], v[70:71], v[62:63] op_sel_hi:[1,0,1]
	s_nop 0
	v_mul_f32_e32 v54, v57, v73
	v_pk_fma_f32 v[64:65], v[56:57], v[72:73], v[54:55] op_sel_hi:[1,1,0] neg_lo:[0,0,1] neg_hi:[0,0,1]
	v_mul_f32_e32 v54, v56, v73
	v_pk_fma_f32 v[70:71], v[56:57], v[72:73], v[54:55] op_sel:[1,0,0] op_sel_hi:[0,1,0]
	v_pk_mul_f32 v[72:73], v[50:51], v[66:67] op_sel:[1,1] op_sel_hi:[0,1]
	v_pk_mul_f32 v[56:57], v[50:51], v[66:67]
	v_pk_fma_f32 v[50:51], v[50:51], v[66:67], v[72:73] op_sel_hi:[1,0,1]
	v_sub_f32_e32 v54, v60, v62
	v_mul_f32_e32 v50, v53, v69
	v_pk_fma_f32 v[66:67], v[52:53], v[68:69], v[50:51] op_sel_hi:[1,1,0] neg_lo:[0,0,1] neg_hi:[0,0,1]
	v_mul_f32_e32 v50, v52, v69
	v_pk_fma_f32 v[68:69], v[52:53], v[68:69], v[50:51] op_sel:[1,0,0] op_sel_hi:[0,1,0]
	v_sub_f32_e32 v50, v56, v72
	v_mov_b32_e32 v56, v64
	v_mov_b32_e32 v57, v70
	v_mov_b32_e32 v52, v66
	v_mov_b32_e32 v53, v68
.LBB0_396:
	v_cvt_pk_bf16_f32 v54, v54, v55
	v_cvt_pk_bf16_f32 v55, v56, v57
	v_cvt_pk_bf16_f32 v56, v50, v51
	v_cvt_pk_bf16_f32 v57, v52, v53
	global_store_dwordx4 v[58:59], v[54:57], off offset:256
	v_add_u32_e32 v58, 0x90, v164
	s_and_b64 vcc, exec, s[36:37]
	v_ashrrev_i32_e32 v59, 31, v58
	s_cbranch_vccnz .LBB0_398
	s_waitcnt vmcnt(2)
	v_mov_b32_e32 v54, v248
	v_mov_b32_e32 v55, v249
	v_mov_b32_e32 v56, v250
	v_mov_b32_e32 v57, v251
	v_mov_b32_e32 v50, v252
	v_mov_b32_e32 v51, v253
	v_mov_b32_e32 v52, v254
	v_mov_b32_e32 v53, v255
	s_branch .LBB0_399

.LBB0_399:
	v_pk_mul_f32 v[60:61], v[152:153], v[48:49] op_sel_hi:[0,1]
	v_pk_mul_f32 v[46:47], v[152:153], v[46:47] op_sel_hi:[0,1]
	v_pk_mul_f32 v[48:49], v[152:153], v[44:45] op_sel_hi:[0,1]
	s_and_b64 vcc, exec, s[36:37]
	v_pk_mul_f32 v[44:45], v[152:153], v[42:43] op_sel_hi:[0,1]
	s_cbranch_vccnz .LBB0_401
	v_add_u32_e32 v240, 0xa0, v164
	v_ashrrev_i32_e32 v241, 31, v240
	v_lshlrev_b64 v[240:241], 8, v[240:241]
	v_lshl_add_u64 v[240:241], v[146:147], 0, v[240:241]
	global_load_dwordx4 v[248:251], v[240:241], off
	global_load_dwordx4 v[252:255], v[240:241], off offset:16
	v_pk_mul_f32 v[62:63], v[46:47], v[54:55] op_sel:[1,1] op_sel_hi:[0,1]
	v_pk_mul_f32 v[42:43], v[46:47], v[54:55]
	v_pk_fma_f32 v[46:47], v[46:47], v[54:55], v[62:63] op_sel_hi:[1,0,1]
	v_pk_mul_f32 v[68:69], v[44:45], v[50:51] op_sel:[1,1] op_sel_hi:[0,1]
	v_mul_f32_e32 v46, v61, v57
	v_pk_fma_f32 v[64:65], v[60:61], v[56:57], v[46:47] op_sel_hi:[1,1,0] neg_lo:[0,0,1] neg_hi:[0,0,1]
	v_mul_f32_e32 v46, v60, v57
	v_pk_fma_f32 v[66:67], v[60:61], v[56:57], v[46:47] op_sel:[1,0,0] op_sel_hi:[0,1,0]
	v_pk_mul_f32 v[60:61], v[44:45], v[50:51]
	v_pk_fma_f32 v[44:45], v[44:45], v[50:51], v[68:69] op_sel_hi:[1,0,1]
	v_sub_f32_e32 v46, v42, v62
	v_mul_f32_e32 v44, v49, v53
	v_pk_fma_f32 v[70:71], v[48:49], v[52:53], v[44:45] op_sel_hi:[1,1,0] neg_lo:[0,0,1] neg_hi:[0,0,1]
	v_mul_f32_e32 v44, v48, v53
	v_pk_fma_f32 v[72:73], v[48:49], v[52:53], v[44:45] op_sel:[1,0,0] op_sel_hi:[0,1,0]
	v_sub_f32_e32 v44, v60, v68
	v_mov_b32_e32 v60, v64
	v_mov_b32_e32 v61, v66
	v_mov_b32_e32 v48, v70
	v_mov_b32_e32 v49, v72
.LBB0_401:
	v_readlane_b32 s8, v245, 21
	v_readlane_b32 s9, v245, 22
	v_mov_b32_e32 v153, v152
	v_pk_mul_f32 v[38:39], v[152:153], v[38:39]
	v_mov_b64_e32 v[42:43], s[8:9]
	v_mad_i64_i32 v[42:43], s[8:9], v58, s33, v[42:43]
	v_cvt_pk_bf16_f32 v58, v46, v47
	v_cvt_pk_bf16_f32 v59, v60, v61
	v_cvt_pk_bf16_f32 v60, v44, v45
	v_mov_b32_e32 v44, v152
	v_mov_b32_e32 v45, v152
	v_lshl_add_u64 v[42:43], v[122:123], 1, v[42:43]
	v_pk_mul_f32 v[40:41], v[44:45], v[40:41]
	v_pk_mul_f32 v[36:37], v[44:45], v[36:37]
	s_and_b64 vcc, exec, s[36:37]
	v_pk_mul_f32 v[34:35], v[152:153], v[34:35]
	v_cvt_pk_bf16_f32 v61, v48, v49
	global_store_dwordx4 v[42:43], v[58:61], off
	s_cbranch_vccnz .LBB0_403
	s_nop 0
	v_pk_mul_f32 v[46:47], v[38:39], v[54:55] op_sel:[1,1] op_sel_hi:[0,1]
	v_pk_mul_f32 v[44:45], v[38:39], v[54:55]
	v_pk_fma_f32 v[38:39], v[38:39], v[54:55], v[46:47] op_sel_hi:[1,0,1]
	s_nop 0
	v_mul_f32_e32 v38, v41, v57
	v_pk_fma_f32 v[48:49], v[40:41], v[56:57], v[38:39] op_sel_hi:[1,1,0] neg_lo:[0,0,1] neg_hi:[0,0,1]
	v_mul_f32_e32 v38, v40, v57
	v_pk_fma_f32 v[54:55], v[40:41], v[56:57], v[38:39] op_sel:[1,0,0] op_sel_hi:[0,1,0]
	v_pk_mul_f32 v[56:57], v[34:35], v[50:51] op_sel:[1,1] op_sel_hi:[0,1]
	v_pk_mul_f32 v[40:41], v[34:35], v[50:51]
	v_pk_fma_f32 v[34:35], v[34:35], v[50:51], v[56:57] op_sel_hi:[1,0,1]
	v_sub_f32_e32 v38, v44, v46
	v_mul_f32_e32 v34, v37, v53
	v_pk_fma_f32 v[50:51], v[36:37], v[52:53], v[34:35] op_sel_hi:[1,1,0] neg_lo:[0,0,1] neg_hi:[0,0,1]
	v_mul_f32_e32 v34, v36, v53
	v_pk_fma_f32 v[52:53], v[36:37], v[52:53], v[34:35] op_sel:[1,0,0] op_sel_hi:[0,1,0]
	v_sub_f32_e32 v34, v40, v56
	v_mov_b32_e32 v40, v48
	v_mov_b32_e32 v41, v54
	v_mov_b32_e32 v36, v50
	v_mov_b32_e32 v37, v52
.LBB0_403:
	v_cvt_pk_bf16_f32 v38, v38, v39
	v_cvt_pk_bf16_f32 v39, v40, v41
	v_cvt_pk_bf16_f32 v40, v34, v35
	v_cvt_pk_bf16_f32 v41, v36, v37
	global_store_dwordx4 v[42:43], v[38:41], off offset:256
	v_add_u32_e32 v42, 0xa0, v164
	s_and_b64 vcc, exec, s[36:37]
	v_ashrrev_i32_e32 v43, 31, v42
	s_cbranch_vccnz .LBB0_405
	s_waitcnt vmcnt(2)
	v_mov_b32_e32 v38, v248
	v_mov_b32_e32 v39, v249
	v_mov_b32_e32 v40, v250
	v_mov_b32_e32 v41, v251
	v_mov_b32_e32 v34, v252
	v_mov_b32_e32 v35, v253
	v_mov_b32_e32 v36, v254
	v_mov_b32_e32 v37, v255
	s_branch .LBB0_406

.LBB0_406:
	v_pk_mul_f32 v[44:45], v[144:145], v[32:33] op_sel_hi:[0,1]
	v_pk_mul_f32 v[30:31], v[144:145], v[30:31] op_sel_hi:[0,1]
	v_pk_mul_f32 v[32:33], v[144:145], v[28:29] op_sel_hi:[0,1]
	s_and_b64 vcc, exec, s[36:37]
	v_pk_mul_f32 v[28:29], v[144:145], v[26:27] op_sel_hi:[0,1]
	s_cbranch_vccnz .LBB0_408
	v_add_u32_e32 v240, 0xb0, v164
	v_ashrrev_i32_e32 v241, 31, v240
	v_lshlrev_b64 v[240:241], 8, v[240:241]
	v_lshl_add_u64 v[240:241], v[146:147], 0, v[240:241]
	global_load_dwordx4 v[248:251], v[240:241], off
	global_load_dwordx4 v[252:255], v[240:241], off offset:16
	v_pk_mul_f32 v[46:47], v[30:31], v[38:39] op_sel:[1,1] op_sel_hi:[0,1]
	v_pk_mul_f32 v[26:27], v[30:31], v[38:39]
	v_pk_fma_f32 v[30:31], v[30:31], v[38:39], v[46:47] op_sel_hi:[1,0,1]
	v_pk_mul_f32 v[52:53], v[28:29], v[34:35] op_sel:[1,1] op_sel_hi:[0,1]
	v_mul_f32_e32 v30, v45, v41
	v_pk_fma_f32 v[48:49], v[44:45], v[40:41], v[30:31] op_sel_hi:[1,1,0] neg_lo:[0,0,1] neg_hi:[0,0,1]
	v_mul_f32_e32 v30, v44, v41
	v_pk_fma_f32 v[50:51], v[44:45], v[40:41], v[30:31] op_sel:[1,0,0] op_sel_hi:[0,1,0]
	v_pk_mul_f32 v[44:45], v[28:29], v[34:35]
	v_pk_fma_f32 v[28:29], v[28:29], v[34:35], v[52:53] op_sel_hi:[1,0,1]
	v_sub_f32_e32 v30, v26, v46
	v_mul_f32_e32 v28, v33, v37
	v_pk_fma_f32 v[54:55], v[32:33], v[36:37], v[28:29] op_sel_hi:[1,1,0] neg_lo:[0,0,1] neg_hi:[0,0,1]
	v_mul_f32_e32 v28, v32, v37
	v_pk_fma_f32 v[56:57], v[32:33], v[36:37], v[28:29] op_sel:[1,0,0] op_sel_hi:[0,1,0]
	v_sub_f32_e32 v28, v44, v52
	v_mov_b32_e32 v44, v48
	v_mov_b32_e32 v45, v50
	v_mov_b32_e32 v32, v54
	v_mov_b32_e32 v33, v56
.LBB0_408:
	v_readlane_b32 s8, v245, 21
	v_readlane_b32 s9, v245, 22
	v_mov_b32_e32 v46, v144
	v_mov_b32_e32 v47, v144
	v_mov_b64_e32 v[26:27], s[8:9]
	v_mad_i64_i32 v[26:27], s[8:9], v42, s33, v[26:27]
	v_cvt_pk_bf16_f32 v42, v30, v31
	v_cvt_pk_bf16_f32 v43, v44, v45
	v_cvt_pk_bf16_f32 v44, v28, v29
	v_mov_b32_e32 v28, v144
	v_mov_b32_e32 v29, v144
	v_lshl_add_u64 v[26:27], v[122:123], 1, v[26:27]
	v_pk_mul_f32 v[24:25], v[28:29], v[24:25]
	v_pk_mul_f32 v[22:23], v[46:47], v[22:23]
	v_pk_mul_f32 v[20:21], v[28:29], v[20:21]
	s_and_b64 vcc, exec, s[36:37]
	v_pk_mul_f32 v[18:19], v[46:47], v[18:19]
	v_cvt_pk_bf16_f32 v45, v32, v33
	global_store_dwordx4 v[26:27], v[42:45], off
	s_cbranch_vccnz .LBB0_410
	s_nop 0
	v_pk_mul_f32 v[30:31], v[22:23], v[38:39] op_sel:[1,1] op_sel_hi:[0,1]
	v_pk_mul_f32 v[28:29], v[22:23], v[38:39]
	v_pk_fma_f32 v[22:23], v[22:23], v[38:39], v[30:31] op_sel_hi:[1,0,1]
	s_nop 0
	v_mul_f32_e32 v22, v25, v41
	v_pk_fma_f32 v[32:33], v[24:25], v[40:41], v[22:23] op_sel_hi:[1,1,0] neg_lo:[0,0,1] neg_hi:[0,0,1]
	v_mul_f32_e32 v22, v24, v41
	v_pk_fma_f32 v[38:39], v[24:25], v[40:41], v[22:23] op_sel:[1,0,0] op_sel_hi:[0,1,0]
	v_pk_mul_f32 v[40:41], v[18:19], v[34:35] op_sel:[1,1] op_sel_hi:[0,1]
	v_pk_mul_f32 v[24:25], v[18:19], v[34:35]
	v_pk_fma_f32 v[18:19], v[18:19], v[34:35], v[40:41] op_sel_hi:[1,0,1]
	v_sub_f32_e32 v22, v28, v30
	v_mul_f32_e32 v18, v21, v37
	v_pk_fma_f32 v[34:35], v[20:21], v[36:37], v[18:19] op_sel_hi:[1,1,0] neg_lo:[0,0,1] neg_hi:[0,0,1]
	v_mul_f32_e32 v18, v20, v37
	v_pk_fma_f32 v[36:37], v[20:21], v[36:37], v[18:19] op_sel:[1,0,0] op_sel_hi:[0,1,0]
	v_sub_f32_e32 v18, v24, v40
	v_mov_b32_e32 v24, v32
	v_mov_b32_e32 v25, v38
	v_mov_b32_e32 v20, v34
	v_mov_b32_e32 v21, v36
.LBB0_410:
	v_cvt_pk_bf16_f32 v22, v22, v23
	v_cvt_pk_bf16_f32 v23, v24, v25
	v_cvt_pk_bf16_f32 v24, v18, v19
	v_cvt_pk_bf16_f32 v25, v20, v21
	global_store_dwordx4 v[26:27], v[22:25], off offset:256
	v_add_u32_e32 v26, 0xb0, v164
	s_and_b64 vcc, exec, s[36:37]
	v_ashrrev_i32_e32 v27, 31, v26
	s_cbranch_vccnz .LBB0_412
	s_waitcnt vmcnt(2)
	v_mov_b32_e32 v22, v248
	v_mov_b32_e32 v23, v249
	v_mov_b32_e32 v24, v250
	v_mov_b32_e32 v25, v251
	v_mov_b32_e32 v18, v252
	v_mov_b32_e32 v19, v253
	v_mov_b32_e32 v20, v254
	v_mov_b32_e32 v21, v255
	s_branch .LBB0_413

.LBB0_413:
	v_mov_b32_e32 v30, v145
	v_pk_mul_f32 v[28:29], v[30:31], v[16:17] op_sel_hi:[0,1]
	v_pk_mul_f32 v[14:15], v[30:31], v[14:15] op_sel_hi:[0,1]
	v_pk_mul_f32 v[16:17], v[30:31], v[12:13] op_sel_hi:[0,1]
	s_and_b64 vcc, exec, s[36:37]
	v_pk_mul_f32 v[12:13], v[30:31], v[10:11] op_sel_hi:[0,1]
	s_cbranch_vccnz .LBB0_415
	s_nop 0
	v_pk_mul_f32 v[30:31], v[14:15], v[22:23] op_sel:[1,1] op_sel_hi:[0,1]
	v_pk_mul_f32 v[10:11], v[14:15], v[22:23]
	v_pk_fma_f32 v[14:15], v[14:15], v[22:23], v[30:31] op_sel_hi:[1,0,1]
	v_pk_mul_f32 v[36:37], v[12:13], v[18:19] op_sel:[1,1] op_sel_hi:[0,1]
	v_mul_f32_e32 v14, v29, v25
	v_pk_fma_f32 v[32:33], v[28:29], v[24:25], v[14:15] op_sel_hi:[1,1,0] neg_lo:[0,0,1] neg_hi:[0,0,1]
	v_mul_f32_e32 v14, v28, v25
	v_pk_fma_f32 v[34:35], v[28:29], v[24:25], v[14:15] op_sel:[1,0,0] op_sel_hi:[0,1,0]
	v_pk_mul_f32 v[28:29], v[12:13], v[18:19]
	v_pk_fma_f32 v[12:13], v[12:13], v[18:19], v[36:37] op_sel_hi:[1,0,1]
	v_sub_f32_e32 v14, v10, v30
	v_mul_f32_e32 v12, v17, v21
	v_pk_fma_f32 v[38:39], v[16:17], v[20:21], v[12:13] op_sel_hi:[1,1,0] neg_lo:[0,0,1] neg_hi:[0,0,1]
	v_mul_f32_e32 v12, v16, v21
	v_pk_fma_f32 v[40:41], v[16:17], v[20:21], v[12:13] op_sel:[1,0,0] op_sel_hi:[0,1,0]
	v_sub_f32_e32 v12, v28, v36
	v_mov_b32_e32 v28, v32
	v_mov_b32_e32 v29, v34
	v_mov_b32_e32 v16, v38
	v_mov_b32_e32 v17, v40
.LBB0_415:
	v_readlane_b32 s8, v245, 21
	v_readlane_b32 s9, v245, 22
	v_mov_b32_e32 v30, v145
	v_mov_b32_e32 v31, v145
	v_mov_b64_e32 v[10:11], s[8:9]
	v_mad_i64_i32 v[10:11], s[8:9], v26, s33, v[10:11]
	v_mov_b32_e32 v144, v145
	v_lshl_add_u64 v[10:11], v[122:123], 1, v[10:11]
	v_pk_mul_f32 v[8:9], v[144:145], v[8:9]
	v_pk_mul_f32 v[6:7], v[30:31], v[6:7]
	v_pk_mul_f32 v[4:5], v[144:145], v[4:5]
	s_and_b64 vcc, exec, s[36:37]
	v_pk_mul_f32 v[2:3], v[30:31], v[2:3]
	v_cvt_pk_bf16_f32 v26, v14, v15
	v_cvt_pk_bf16_f32 v27, v28, v29
	v_cvt_pk_bf16_f32 v28, v12, v13
	v_cvt_pk_bf16_f32 v29, v16, v17
	global_store_dwordx4 v[10:11], v[26:29], off
	s_cbranch_vccnz .LBB0_417
	s_nop 0
	v_pk_mul_f32 v[14:15], v[6:7], v[22:23] op_sel:[1,1] op_sel_hi:[0,1]
	v_pk_mul_f32 v[12:13], v[6:7], v[22:23]
	v_pk_fma_f32 v[6:7], v[6:7], v[22:23], v[14:15] op_sel_hi:[1,0,1]
	s_nop 0
	v_mul_f32_e32 v6, v9, v25
	v_pk_fma_f32 v[16:17], v[8:9], v[24:25], v[6:7] op_sel_hi:[1,1,0] neg_lo:[0,0,1] neg_hi:[0,0,1]
	v_mul_f32_e32 v6, v8, v25
	v_pk_fma_f32 v[22:23], v[8:9], v[24:25], v[6:7] op_sel:[1,0,0] op_sel_hi:[0,1,0]
	v_pk_mul_f32 v[24:25], v[2:3], v[18:19] op_sel:[1,1] op_sel_hi:[0,1]
	v_pk_mul_f32 v[8:9], v[2:3], v[18:19]
	v_pk_fma_f32 v[2:3], v[2:3], v[18:19], v[24:25] op_sel_hi:[1,0,1]
	v_sub_f32_e32 v6, v12, v14
	v_mul_f32_e32 v2, v5, v21
	v_pk_fma_f32 v[18:19], v[4:5], v[20:21], v[2:3] op_sel_hi:[1,1,0] neg_lo:[0,0,1] neg_hi:[0,0,1]
	v_mul_f32_e32 v2, v4, v21
	v_pk_fma_f32 v[20:21], v[4:5], v[20:21], v[2:3] op_sel:[1,0,0] op_sel_hi:[0,1,0]
	v_sub_f32_e32 v2, v8, v24
	v_mov_b32_e32 v8, v16
	v_mov_b32_e32 v9, v22
	v_mov_b32_e32 v4, v18
	v_mov_b32_e32 v5, v20
